# c12 + more lane-exchange reductions (row-scale table, attention finish, cvt, retention combine incl. packed pairs) converted from ds_bpermute to permlane swaps / fused DPP adds
# speedup vs baseline: 1.0032x; 1.0032x over previous
; DI unsigned pack_bf16(float lo, float hi) { f32v2 f = {lo, hi}; bf16v2 b = __builtin_convertvector(f, bf16v2); return __builtin_bit_cast(unsigned, b); }
; DI float shx(float v, int o) { int l = (int)__builtin_amdgcn_mbcnt_hi(~0u, __builtin_amdgcn_mbcnt_lo(~0u, 0u)); asm volatile("" : "+v"(l)); return __int_as_float(__builtin_amdgcn_ds_bpermute((l ^ o) << 2, __float_as_int(v))); }
; DI float wave_sum(float v) {
; #pragma unroll
;     for (int o = 32; o >= 1; o >>= 1) v += shx(v, o);
;     return v;
; }
; DI void cvt_phase(const float* __restrict__ x, bf16_t* __restrict__ h, float* __restrict__ ss, int rows) {
;     ...
;     for (int row0 = (blockIdx.x * 8 + wave) * RB; row0 < rows; row0 += gridDim.x * 8 * RB) {
;         float4 v[RB][4];
; #pragma unroll
;         for (int r = 0; r < RB; ++r)
; #pragma unroll
;             for (int i = 0; i < 4; ++i) v[r][i] = ((const float4*)(x + (size_t)(row0 + r) * D))[i * 64 + lane];
; #pragma unroll
;         for (int r = 0; r < RB; ++r) {
;             float s2 = 0.f;
; #pragma unroll
;             for (int i = 0; i < 4; ++i) s2 += v[r][i].x * v[r][i].x + v[r][i].y * v[r][i].y + v[r][i].z * v[r][i].z + v[r][i].w * v[r][i].w;
;             s2 = wave_sum(s2);
;             if (lane < 4) *(f32x4*)(ss + (size_t)(row0 + r) * 16 + 4 * lane) = (f32x4){lane == 0 ? s2 : 0.f, 0.f, 0.f, 0.f};
; #pragma unroll
;             for (int i = 0; i < 4; ++i) { uint2 w; w.x = pack_bf16(v[r][i].x, v[r][i].y); w.y = pack_bf16(v[r][i].z, v[r][i].w); *(uint2*)(h + (size_t)(row0 + r) * D + (i * 64 + lane) * 4) = w; }
.LBB0_132:
	v_ashrrev_i32_e32 v69, 31, v68
	v_lshlrev_b64 v[2:3], 12, v[68:69]
	v_lshl_add_u64 v[2:3], v[72:73], 0, v[2:3]
	global_load_dwordx4 v[64:67], v[2:3], off
	global_load_dwordx4 v[60:63], v[2:3], off offset:1024
	global_load_dwordx4 v[56:59], v[2:3], off offset:2048
	global_load_dwordx4 v[52:55], v[2:3], off offset:3072
	v_add_u32_e32 v80, 1, v68
	v_add_u32_e32 v78, 2, v68
	v_add_u32_e32 v76, 3, v68
	v_ashrrev_i32_e32 v81, 31, v80
	v_ashrrev_i32_e32 v79, 31, v78
	v_ashrrev_i32_e32 v77, 31, v76
	v_lshlrev_b64 v[2:3], 12, v[80:81]
	v_lshlrev_b64 v[4:5], 12, v[78:79]
	v_lshlrev_b64 v[6:7], 12, v[76:77]
	v_lshl_add_u64 v[2:3], v[72:73], 0, v[2:3]
	v_lshl_add_u64 v[4:5], v[72:73], 0, v[4:5]
	v_lshl_add_u64 v[6:7], v[72:73], 0, v[6:7]
	global_load_dwordx4 v[48:51], v[2:3], off
	global_load_dwordx4 v[44:47], v[2:3], off offset:1024
	global_load_dwordx4 v[40:43], v[2:3], off offset:2048
	global_load_dwordx4 v[36:39], v[2:3], off offset:3072
	global_load_dwordx4 v[32:35], v[4:5], off
	global_load_dwordx4 v[28:31], v[4:5], off offset:1024
	global_load_dwordx4 v[24:27], v[4:5], off offset:2048
	global_load_dwordx4 v[20:23], v[4:5], off offset:3072
	global_load_dwordx4 v[16:19], v[6:7], off
	global_load_dwordx4 v[12:15], v[6:7], off offset:1024
	global_load_dwordx4 v[8:11], v[6:7], off offset:2048
	s_nop 0
	global_load_dwordx4 v[4:7], v[6:7], off offset:3072
	s_waitcnt vmcnt(15)
	v_pk_mul_f32 v[2:3], v[64:65], v[64:65]
	s_waitcnt vmcnt(14)
	v_pk_mul_f32 v[84:85], v[60:61], v[60:61]
	v_pk_mul_f32 v[82:83], v[66:67], v[66:67]
	v_pk_mul_f32 v[86:87], v[62:63], v[62:63]
	s_waitcnt vmcnt(13)
	v_pk_mul_f32 v[88:89], v[56:57], v[56:57]
	v_add_f32_e32 v84, v84, v85
	v_add_f32_e32 v2, v2, v3
	v_pk_mul_f32 v[90:91], v[58:59], v[58:59]
	s_waitcnt vmcnt(12)
	v_pk_mul_f32 v[92:93], v[52:53], v[52:53]
	v_add_f32_e32 v3, v88, v89
	v_add_f32_e32 v84, v84, v86
	v_add_f32_e32 v2, v2, v82
	v_pk_mul_f32 v[94:95], v[54:55], v[54:55]
	v_add_f32_e32 v85, v92, v93
	v_add_f32_e32 v3, v3, v90
	v_add_f32_e32 v84, v84, v87
	v_add_f32_e32 v2, v2, v83
	v_add_f32_e32 v82, v85, v94
	v_add_f32_e32 v3, v3, v91
	v_add_f32_e32 v2, v2, v84
	v_add_f32_e32 v82, v82, v95
	v_add_f32_e32 v2, v2, v3
	v_add_f32_e32 v2, v2, v82
	v_mov_b32_e32 v0, v2
	s_nop 1
	v_permlane32_swap_b32_e32 v0, v2
	s_waitcnt lgkmcnt(0)
	v_add_f32_e32 v0, v2, v0
	v_mov_b32_e32 v2, v0
	s_nop 1
	v_permlane16_swap_b32_e32 v2, v0
	s_waitcnt lgkmcnt(0)
	v_add_f32_e32 v0, v0, v2
	s_waitcnt lgkmcnt(0)
	s_nop 1
	v_add_f32_dpp v0, v0, v0 row_ror:8 row_mask:0xf bank_mask:0xf
	s_waitcnt lgkmcnt(0)
	s_nop 1
	v_add_f32_dpp v0, v0, v0 row_ror:4 row_mask:0xf bank_mask:0xf
	v_mov_b32_e32 v3, v205
	s_waitcnt lgkmcnt(0)
	s_nop 1
	v_add_f32_dpp v0, v0, v0 quad_perm:[2,3,0,1] row_mask:0xf bank_mask:0xf
	v_lshlrev_b32_e32 v3, 2, v3
	v_xor_b32_e32 v2, 4, v3
	ds_bpermute_b32 v2, v2, v0
	s_and_saveexec_b64 s[4:5], vcc
	s_cbranch_execz .LBB0_134
	v_lshlrev_b64 v[82:83], 6, v[68:69]
	s_waitcnt lgkmcnt(0)
	v_add_f32_e32 v0, v0, v2
	v_lshl_add_u64 v[82:83], v[70:71], 0, v[82:83]
	v_cndmask_b32_e64 v0, 0, v0, s[0:1]
	v_mov_b32_e32 v2, v1
	v_mov_b32_e32 v3, v1
	global_store_dwordx4 v[82:83], v[0:3], off

; DI void ret_combine_phase(const bf16_t* __restrict__ R, const bf16_t* __restrict__ P, bf16_t* __restrict__ Oo, int T) {
;     ...
;     for (int it0 = blockIdx.x * 8 + wave; it0 < T * 4; it0 += 2 * stride) {
;         u32x4 ra[2], rb[2], rg[2]; size_t off[2];
; #pragma unroll
;         for (int u = 0; u < 2; ++u) {
;             const int it = (it0 + u * stride < T * 4) ? it0 + u * stride : it0, tok = it >> 2, hh = it & 3;
;             off[u] = (size_t)tok * RMIX + hh * 512 + lane * 8;
;             ra[u] = *(const u32x4*)(R + off[u]); rb[u] = *(const u32x4*)(R + (size_t)TG * RMIX + off[u]);
;             rg[u] = *(const u32x4*)(P + (size_t)tok * RIN + 4096 + hh * 512 + lane * 8);
;         }
; #pragma unroll
;         for (int u = 0; u < 2; ++u) {
;             float a[8], c[8], g[8];
;             unpack8(ra[u], a); unpack8(rb[u], c); unpack8(rg[u], g);
;             float s = 0.f;
; #pragma unroll
;             for (int e = 0; e < 8; ++e) { a[e] += c[e]; s += a[e]; }
;     ...
;             for (int e = 0; e < 8; ++e) { const float sg = g[e] / (1.0f + __expf(-g[e])); o[e] = sg * a[e] * rstd; }
.LBB0_954:
	v_ashrrev_i32_e32 v4, 2, v2
	v_ashrrev_i32_e32 v5, 31, v4
	v_lshlrev_b64 v[6:7], 11, v[4:5]
	v_and_b32_e32 v0, 0x600, v27
	v_mov_b64_e32 v[10:11], s[12:13]
	v_or_b32_e32 v3, v6, v0
	v_mad_i64_i32 v[4:5], s[0:1], v4, s76, v[10:11]
	v_lshlrev_b32_e32 v0, 1, v0
	v_lshl_add_u64 v[4:5], v[4:5], 0, v[0:1]
	v_lshlrev_b32_e32 v0, 1, v26
	v_lshl_add_u64 v[4:5], v[4:5], 0, v[0:1]
	v_add_co_u32_e32 v4, vcc, s27, v4
	v_add_u32_e32 v38, s20, v2
	s_nop 0
	v_addc_co_u32_e32 v5, vcc, 0, v5, vcc
	v_cmp_gt_i32_e32 vcc, s21, v38
	global_load_dwordx4 v[22:25], v[4:5], off
	v_or_b32_e32 v6, v3, v26
	v_cndmask_b32_e32 v4, v2, v38, vcc
	v_ashrrev_i32_e32 v12, 2, v4
	v_ashrrev_i32_e32 v13, 31, v12
	v_lshlrev_b32_e32 v4, 9, v4
	v_lshlrev_b64 v[2:3], 11, v[12:13]
	v_and_b32_e32 v13, 0x600, v4
	v_or_b32_e32 v2, v2, v13
	v_or_b32_e32 v2, v2, v26
	s_waitcnt vmcnt(9)
	v_lshlrev_b64 v[36:37], 1, v[6:7]
	v_lshlrev_b64 v[28:29], 1, v[2:3]
	v_lshl_add_u64 v[6:7], s[10:11], 0, v[36:37]
	v_lshl_add_u64 v[2:3], s[10:11], 0, v[28:29]
	global_load_dwordx4 v[14:17], v[6:7], off
	v_mad_i64_i32 v[10:11], s[0:1], v12, s76, v[10:11]
	global_load_dwordx4 v[2:5], v[2:3], off
	v_lshl_add_u64 v[6:7], s[16:17], 0, v[36:37]
	global_load_dwordx4 v[18:21], v[6:7], off
	v_lshlrev_b32_e32 v12, 1, v13
	v_mov_b32_e32 v13, v1
	v_lshl_add_u64 v[10:11], v[10:11], 0, v[12:13]
	v_lshl_add_u64 v[10:11], v[10:11], 0, v[0:1]
	v_add_co_u32_e32 v10, vcc, s27, v10
	v_lshl_add_u64 v[6:7], s[16:17], 0, v[28:29]
	s_nop 0
	v_addc_co_u32_e32 v11, vcc, 0, v11, vcc
	v_mov_b32_e32 v0, v205
	global_load_dwordx4 v[6:9], v[6:7], off
	v_mov_b32_e32 v30, v205
	global_load_dwordx4 v[10:13], v[10:11], off
	v_add_u32_e32 v27, s26, v27
	v_lshlrev_b32_e32 v0, 2, v0
	v_xor_b32_e32 v34, 0x80, v0
	v_mov_b32_e32 v0, v205
	s_waitcnt vmcnt(5)
	v_lshlrev_b32_e32 v52, 16, v25
	v_lshlrev_b32_e32 v0, 2, v0
	v_xor_b32_e32 v35, 64, v0
	v_mov_b32_e32 v0, v205
	v_and_b32_e32 v53, 0xffff0000, v25
	v_lshlrev_b32_e32 v0, 2, v0
	v_xor_b32_e32 v48, 32, v0
	v_mov_b32_e32 v0, v205
	v_lshlrev_b32_e32 v25, 16, v24
	v_lshlrev_b32_e32 v0, 2, v0
	v_xor_b32_e32 v49, 16, v0
	v_mov_b32_e32 v0, v205
	s_waitcnt vmcnt(4)
	v_and_b32_e32 v31, 0xffff0000, v17
	v_lshlrev_b32_e32 v0, 2, v0
	v_xor_b32_e32 v50, 8, v0
	v_mov_b32_e32 v0, v205
	s_waitcnt vmcnt(2)
	v_lshlrev_b32_e32 v32, 16, v21
	v_lshlrev_b32_e32 v0, 2, v0
	v_xor_b32_e32 v51, 4, v0
	v_mov_b32_e32 v0, v205
	v_and_b32_e32 v33, 0xffff0000, v21
	v_lshlrev_b32_e32 v30, 2, v30
	v_xor_b32_e32 v39, 64, v30
	v_mov_b32_e32 v30, v205
	v_and_b32_e32 v24, 0xffff0000, v24
	v_lshlrev_b32_e32 v30, 2, v30
	v_xor_b32_e32 v40, 32, v30
	v_mov_b32_e32 v30, v205
	v_mul_f32_e32 v21, 0xbfb8aa3b, v24
	v_lshlrev_b32_e32 v30, 2, v30
	v_xor_b32_e32 v41, 16, v30
	v_mov_b32_e32 v30, v205
	v_exp_f32_e32 v21, v21
	v_lshlrev_b32_e32 v30, 2, v30
	v_xor_b32_e32 v42, 8, v30
	v_mov_b32_e32 v30, v205
	s_waitcnt vmcnt(0)
	v_lshlrev_b32_e32 v60, 16, v13
	v_lshlrev_b32_e32 v30, 2, v30
	v_xor_b32_e32 v43, 4, v30
	v_lshlrev_b32_e32 v30, 16, v17
	v_pk_add_f32 v[44:45], v[30:31], v[32:33]
	v_lshlrev_b32_e32 v30, 16, v16
	v_and_b32_e32 v31, 0xffff0000, v16
	v_lshlrev_b32_e32 v16, 16, v20
	v_and_b32_e32 v17, 0xffff0000, v20
	v_mul_f32_e32 v20, 0xbfb8aa3b, v25
	v_exp_f32_e32 v20, v20
	v_pk_add_f32 v[16:17], v[30:31], v[16:17]
	v_and_b32_e32 v61, 0xffff0000, v13
	v_lshlrev_b32_e32 v0, 2, v0
	v_pk_add_f32 v[20:21], v[20:21], 1.0 op_sel_hi:[1,0]
	v_xor_b32_e32 v0, 0x80, v0
	v_div_scale_f32 v30, s[0:1], v21, v21, v24
	v_rcp_f32_e32 v31, v30
	s_nop 0
	v_fma_f32 v32, -v30, v31, 1.0
	v_fmac_f32_e32 v31, v32, v31
	v_div_scale_f32 v32, vcc, v24, v21, v24
	v_mul_f32_e32 v33, v32, v31
	v_fma_f32 v46, -v30, v33, v32
	v_fmac_f32_e32 v33, v46, v31
	v_fma_f32 v30, -v30, v33, v32
	v_div_fmas_f32 v30, v30, v31, v33
	v_div_fixup_f32 v21, v30, v21, v24
	v_div_scale_f32 v24, s[0:1], v20, v20, v25
	v_rcp_f32_e32 v30, v24
	s_nop 0
	v_fma_f32 v31, -v24, v30, 1.0
	v_fmac_f32_e32 v30, v31, v30
	v_div_scale_f32 v31, vcc, v25, v20, v25
	v_mul_f32_e32 v32, v31, v30
	v_fma_f32 v33, -v24, v32, v31
	v_fmac_f32_e32 v32, v33, v30
	v_fma_f32 v24, -v24, v32, v31
	v_div_fmas_f32 v24, v24, v30, v32
	v_div_fixup_f32 v20, v24, v20, v25
	v_lshlrev_b32_e32 v24, 16, v15
	v_and_b32_e32 v25, 0xffff0000, v15
	v_lshlrev_b32_e32 v15, 16, v23
	v_lshlrev_b32_e32 v30, 16, v19
	v_and_b32_e32 v31, 0xffff0000, v19
	v_and_b32_e32 v19, 0xffff0000, v23
	v_mul_f32_e32 v23, 0xbfb8aa3b, v15
	v_pk_add_f32 v[24:25], v[24:25], v[30:31]
	v_exp_f32_e32 v30, v23
	v_mul_f32_e32 v23, 0xbfb8aa3b, v19
	v_exp_f32_e32 v31, v23
	s_nop 0
	v_pk_add_f32 v[30:31], v[30:31], 1.0 op_sel_hi:[1,0]
	s_nop 0
	v_div_scale_f32 v23, s[0:1], v31, v31, v19
	v_rcp_f32_e32 v32, v23
	s_nop 0
	v_fma_f32 v33, -v23, v32, 1.0
	v_fmac_f32_e32 v32, v33, v32
	v_div_scale_f32 v33, vcc, v19, v31, v19
	v_mul_f32_e32 v46, v33, v32
	v_fma_f32 v47, -v23, v46, v33
	v_fmac_f32_e32 v46, v47, v32
	v_fma_f32 v23, -v23, v46, v33
	v_div_fmas_f32 v23, v23, v32, v46
	v_div_fixup_f32 v47, v23, v31, v19
	v_div_scale_f32 v19, s[0:1], v30, v30, v15
	v_rcp_f32_e32 v23, v19
	s_nop 0
	v_fma_f32 v31, -v19, v23, 1.0
	v_fmac_f32_e32 v23, v31, v23
	v_div_scale_f32 v31, vcc, v15, v30, v15
	v_mul_f32_e32 v32, v31, v23
	v_fma_f32 v33, -v19, v32, v31
	v_fmac_f32_e32 v32, v33, v23
	v_fma_f32 v19, -v19, v32, v31
	v_div_fmas_f32 v19, v19, v23, v32
	v_div_fixup_f32 v46, v19, v30, v15
	v_lshlrev_b32_e32 v30, 16, v14
	v_and_b32_e32 v31, 0xffff0000, v14
	v_lshlrev_b32_e32 v14, 16, v18
	v_and_b32_e32 v15, 0xffff0000, v18
	v_pk_add_f32 v[14:15], v[30:31], v[14:15]
	v_lshlrev_b32_e32 v23, 16, v22
	v_and_b32_e32 v22, 0xffff0000, v22
	v_add_f32_e32 v18, 0, v14
	v_add_f32_e32 v30, v15, v18
	v_mul_f32_e32 v18, 0xbfb8aa3b, v23
	v_mul_f32_e32 v19, 0xbfb8aa3b, v22
	v_exp_f32_e32 v18, v18
	v_exp_f32_e32 v19, v19
	s_nop 0
	v_pk_add_f32 v[18:19], v[18:19], 1.0 op_sel_hi:[1,0]
	s_nop 0
	v_div_scale_f32 v31, s[0:1], v19, v19, v22
	v_rcp_f32_e32 v32, v31
	s_nop 0
	v_fma_f32 v33, -v31, v32, 1.0
	v_fmac_f32_e32 v32, v33, v32
	v_div_scale_f32 v33, vcc, v22, v19, v22
	v_mul_f32_e32 v54, v33, v32
	v_fma_f32 v55, -v31, v54, v33
	v_fmac_f32_e32 v54, v55, v32
	v_fma_f32 v31, -v31, v54, v33
	v_div_fmas_f32 v31, v31, v32, v54
	v_div_fixup_f32 v19, v31, v19, v22
	v_div_scale_f32 v22, s[0:1], v18, v18, v23
	v_rcp_f32_e32 v31, v22
	s_nop 0
	v_fma_f32 v32, -v22, v31, 1.0
	v_fmac_f32_e32 v31, v32, v31
	v_div_scale_f32 v32, vcc, v23, v18, v23
	v_mul_f32_e32 v33, v32, v31
	v_fma_f32 v54, -v22, v33, v32
	v_fmac_f32_e32 v33, v54, v31
	v_fma_f32 v22, -v22, v33, v32
	v_div_fmas_f32 v22, v22, v31, v33
	v_div_fixup_f32 v18, v22, v18, v23
	v_add_f32_e32 v22, v24, v30
	v_add_f32_e32 v22, v25, v22
	v_add_f32_e32 v22, v16, v22
	v_add_f32_e32 v22, v17, v22
	v_add_f32_e32 v22, v44, v22
	v_add_f32_e32 v22, v45, v22
	v_mov_b32_e32 v23, v22
	s_nop 1
	v_permlane32_swap_b32_e32 v23, v22
	s_waitcnt lgkmcnt(0)
; DI void ret_combine_phase(const bf16_t* __restrict__ R, const bf16_t* __restrict__ P, bf16_t* __restrict__ Oo, int T) {
;     ...
;         for (int u = 0; u < 2; ++u) {
;             float a[8], c[8], g[8];
;             unpack8(ra[u], a); unpack8(rb[u], c); unpack8(rg[u], g);
;             float s = 0.f;
; #pragma unroll
;             for (int e = 0; e < 8; ++e) { a[e] += c[e]; s += a[e]; }
;             const float mu = wave_sum(s) * (1.0f / 512.f);
;             float v = 0.f;
; #pragma unroll
;             for (int e = 0; e < 8; ++e) { a[e] -= mu; v += a[e] * a[e]; }
;             const float rstd = rsqrtf(wave_sum(v) * (1.0f / 512.f) + 1e-6f);
;     ...
;             for (int e = 0; e < 8; ++e) { const float sg = g[e] / (1.0f + __expf(-g[e])); o[e] = sg * a[e] * rstd; }
	v_add_f32_e32 v22, v22, v23
	v_mov_b32_e32 v23, v22
	s_nop 1
	v_permlane16_swap_b32_e32 v23, v22
	s_waitcnt lgkmcnt(0)
	v_add_f32_e32 v22, v22, v23
	s_waitcnt lgkmcnt(0)
	s_nop 1
	v_add_f32_dpp v22, v22, v22 row_ror:8 row_mask:0xf bank_mask:0xf
	s_waitcnt lgkmcnt(0)
	s_nop 1
	v_add_f32_dpp v22, v22, v22 row_ror:4 row_mask:0xf bank_mask:0xf
	s_waitcnt lgkmcnt(0)
	s_nop 1
	v_add_f32_dpp v22, v22, v22 quad_perm:[2,3,0,1] row_mask:0xf bank_mask:0xf
	s_waitcnt lgkmcnt(0)
	s_nop 1
	v_add_f32_dpp v22, v22, v22 quad_perm:[1,0,3,2] row_mask:0xf bank_mask:0xf
	v_mul_f32_e32 v22, 0x3b000000, v22
	v_pk_add_f32 v[34:35], v[14:15], v[22:23] op_sel_hi:[1,0] neg_lo:[0,1] neg_hi:[0,1]
	v_pk_add_f32 v[48:49], v[16:17], v[22:23] op_sel_hi:[1,0] neg_lo:[0,1] neg_hi:[0,1]
	v_pk_mul_f32 v[14:15], v[18:19], v[34:35]
	v_pk_mul_f32 v[18:19], v[20:21], v[48:49]
	v_mul_f32_e32 v20, 0xbfb8aa3b, v52
	v_mul_f32_e32 v21, 0xbfb8aa3b, v53
	v_exp_f32_e32 v20, v20
	v_exp_f32_e32 v21, v21
	v_pk_add_f32 v[32:33], v[24:25], v[22:23] op_sel_hi:[1,0] neg_lo:[0,1] neg_hi:[0,1]
	v_pk_add_f32 v[22:23], v[44:45], v[22:23] op_sel_hi:[1,0] neg_lo:[0,1] neg_hi:[0,1]
	v_pk_mul_f32 v[16:17], v[46:47], v[32:33]
	v_pk_add_f32 v[20:21], v[20:21], 1.0 op_sel_hi:[1,0]
	v_pk_mul_f32 v[30:31], v[48:49], v[48:49]
	v_div_scale_f32 v44, s[0:1], v21, v21, v53
	v_rcp_f32_e32 v45, v44
	v_pk_mul_f32 v[24:25], v[22:23], v[22:23]
	v_fma_f32 v46, -v44, v45, 1.0
	v_fmac_f32_e32 v45, v46, v45
	v_div_scale_f32 v46, vcc, v53, v21, v53
	v_mul_f32_e32 v47, v46, v45
	v_fma_f32 v48, -v44, v47, v46
	v_fmac_f32_e32 v47, v48, v45
	v_fma_f32 v44, -v44, v47, v46
	v_div_fmas_f32 v44, v44, v45, v47
	v_div_fixup_f32 v21, v44, v21, v53
	v_div_scale_f32 v44, s[0:1], v20, v20, v52
	v_rcp_f32_e32 v45, v44
	s_nop 0
	v_fma_f32 v46, -v44, v45, 1.0
	v_fmac_f32_e32 v45, v46, v45
	v_div_scale_f32 v46, vcc, v52, v20, v52
	v_mul_f32_e32 v47, v46, v45
	v_fma_f32 v48, -v44, v47, v46
	v_fmac_f32_e32 v47, v48, v45
	v_fma_f32 v44, -v44, v47, v46
	v_div_fmas_f32 v44, v44, v45, v47
	v_div_fixup_f32 v20, v44, v20, v52
	v_pk_mul_f32 v[22:23], v[20:21], v[22:23]
	v_lshl_add_u64 v[20:21], s[14:15], 0, v[36:37]
	v_mov_b32_e32 v36, v205
	v_and_b32_e32 v37, 0xffff0000, v5
	v_lshlrev_b32_e32 v36, 2, v36
	v_xor_b32_e32 v48, 0x80, v36
	v_mov_b32_e32 v36, v205
	v_lshlrev_b32_e32 v44, 16, v9
	v_lshlrev_b32_e32 v36, 2, v36
	v_xor_b32_e32 v49, 64, v36
	v_mov_b32_e32 v36, v205
	v_and_b32_e32 v45, 0xffff0000, v9
	v_lshlrev_b32_e32 v36, 2, v36
	v_xor_b32_e32 v50, 32, v36
	v_mov_b32_e32 v36, v205
	v_and_b32_e32 v9, 0xffff0000, v12
	v_lshlrev_b32_e32 v36, 2, v36
	v_xor_b32_e32 v51, 16, v36
	v_mov_b32_e32 v36, v205
	s_nop 0
	v_lshlrev_b32_e32 v36, 2, v36
	v_xor_b32_e32 v52, 8, v36
	v_mov_b32_e32 v36, v205
	s_nop 0
	v_lshlrev_b32_e32 v36, 2, v36
	v_xor_b32_e32 v53, 4, v36
	v_mov_b32_e32 v36, v205
	s_nop 0
	v_lshlrev_b32_e32 v36, 2, v36
	v_xor_b32_e32 v54, 0x80, v36
	v_mov_b32_e32 v36, v205
	s_nop 0
	v_lshlrev_b32_e32 v36, 2, v36
	v_xor_b32_e32 v55, 64, v36
	v_mov_b32_e32 v36, v205
	s_nop 0
	v_lshlrev_b32_e32 v36, 2, v36
	v_xor_b32_e32 v56, 32, v36
	v_mov_b32_e32 v36, v205
	s_nop 0
	v_lshlrev_b32_e32 v36, 2, v36
	v_xor_b32_e32 v57, 16, v36
	v_mov_b32_e32 v36, v205
	s_nop 0
	v_lshlrev_b32_e32 v36, 2, v36
	v_xor_b32_e32 v58, 8, v36
	v_mov_b32_e32 v36, v205
	s_nop 0
	v_lshlrev_b32_e32 v36, 2, v36
	v_xor_b32_e32 v59, 4, v36
	v_lshlrev_b32_e32 v36, 16, v5
	v_pk_add_f32 v[36:37], v[36:37], v[44:45]
	v_lshlrev_b32_e32 v44, 16, v4
	v_and_b32_e32 v45, 0xffff0000, v4
	v_lshlrev_b32_e32 v4, 16, v8
	v_and_b32_e32 v5, 0xffff0000, v8
	v_lshlrev_b32_e32 v8, 16, v12
	v_pk_add_f32 v[12:13], v[44:45], v[4:5]
	v_mul_f32_e32 v4, 0xbfb8aa3b, v8
	v_mul_f32_e32 v5, 0xbfb8aa3b, v9
	v_exp_f32_e32 v4, v4
	v_exp_f32_e32 v5, v5
	s_nop 0
	v_pk_add_f32 v[4:5], v[4:5], 1.0 op_sel_hi:[1,0]
	s_nop 0
	v_div_scale_f32 v44, s[0:1], v5, v5, v9
	v_rcp_f32_e32 v45, v44
	s_nop 0
	v_fma_f32 v46, -v44, v45, 1.0
	v_fmac_f32_e32 v45, v46, v45
	v_div_scale_f32 v46, vcc, v9, v5, v9
	v_mul_f32_e32 v47, v46, v45
	v_fma_f32 v62, -v44, v47, v46
	v_fmac_f32_e32 v47, v62, v45
	v_fma_f32 v44, -v44, v47, v46
	v_div_fmas_f32 v44, v44, v45, v47
	v_div_fixup_f32 v5, v44, v5, v9
	v_div_scale_f32 v9, s[0:1], v4, v4, v8
	v_rcp_f32_e32 v44, v9
	s_nop 0
	v_fma_f32 v45, -v9, v44, 1.0
	v_fmac_f32_e32 v44, v45, v44
	v_div_scale_f32 v45, vcc, v8, v4, v8
	v_mul_f32_e32 v46, v45, v44
	v_fma_f32 v47, -v9, v46, v45
	v_fmac_f32_e32 v46, v47, v44
	v_fma_f32 v9, -v9, v46, v45
	v_div_fmas_f32 v9, v9, v44, v46
	v_div_fixup_f32 v4, v9, v4, v8
	v_lshlrev_b32_e32 v8, 16, v3
	v_and_b32_e32 v9, 0xffff0000, v3
	v_lshlrev_b32_e32 v44, 16, v7
	v_and_b32_e32 v45, 0xffff0000, v7
	v_lshlrev_b32_e32 v3, 16, v11
	v_and_b32_e32 v7, 0xffff0000, v11
	v_pk_add_f32 v[44:45], v[8:9], v[44:45]
	v_mul_f32_e32 v8, 0xbfb8aa3b, v3
	v_mul_f32_e32 v9, 0xbfb8aa3b, v7
	v_exp_f32_e32 v8, v8
	v_exp_f32_e32 v9, v9
	s_nop 0
	v_pk_add_f32 v[8:9], v[8:9], 1.0 op_sel_hi:[1,0]
	s_nop 0
	v_div_scale_f32 v11, s[0:1], v9, v9, v7
	v_rcp_f32_e32 v46, v11
	s_nop 0
	v_fma_f32 v47, -v11, v46, 1.0
	v_fmac_f32_e32 v46, v47, v46
	v_div_scale_f32 v47, vcc, v7, v9, v7
	v_mul_f32_e32 v62, v47, v46
	v_fma_f32 v63, -v11, v62, v47
	v_fmac_f32_e32 v62, v63, v46
	v_fma_f32 v11, -v11, v62, v47
	v_div_fmas_f32 v11, v11, v46, v62
	v_div_fixup_f32 v9, v11, v9, v7
	v_div_scale_f32 v7, s[0:1], v8, v8, v3
	v_rcp_f32_e32 v11, v7
	s_nop 0
	v_fma_f32 v46, -v7, v11, 1.0
	v_fmac_f32_e32 v11, v46, v11
	v_div_scale_f32 v46, vcc, v3, v8, v3
	v_mul_f32_e32 v47, v46, v11
	v_fma_f32 v62, -v7, v47, v46
	v_fmac_f32_e32 v47, v62, v11
	v_fma_f32 v7, -v7, v47, v46
	v_div_fmas_f32 v7, v7, v11, v47
; DI bf16x8 pack8(const float* v) { u32x4 w; w.x = pack_bf16(v[0], v[1]); w.y = pack_bf16(v[2], v[3]); w.z = pack_bf16(v[4], v[5]); w.w = pack_bf16(v[6], v[7]); return __builtin_bit_cast(bf16x8, w); }
; DI void ret_combine_phase(const bf16_t* __restrict__ R, const bf16_t* __restrict__ P, bf16_t* __restrict__ Oo, int T) {
;     ...
;             unpack8(ra[u], a); unpack8(rb[u], c); unpack8(rg[u], g);
;             float s = 0.f;
; #pragma unroll
;             for (int e = 0; e < 8; ++e) { a[e] += c[e]; s += a[e]; }
;             const float mu = wave_sum(s) * (1.0f / 512.f);
;             float v = 0.f;
; #pragma unroll
;             for (int e = 0; e < 8; ++e) { a[e] -= mu; v += a[e] * a[e]; }
;             const float rstd = rsqrtf(wave_sum(v) * (1.0f / 512.f) + 1e-6f);
;             float o[8];
; #pragma unroll
;             for (int e = 0; e < 8; ++e) { const float sg = g[e] / (1.0f + __expf(-g[e])); o[e] = sg * a[e] * rstd; }
;             *(bf16x8*)(Oo + off[u]) = pack8(o);
;         }
	v_div_fixup_f32 v8, v7, v8, v3
	v_lshlrev_b32_e32 v46, 16, v2
	v_and_b32_e32 v47, 0xffff0000, v2
	v_lshlrev_b32_e32 v2, 16, v6
	v_and_b32_e32 v3, 0xffff0000, v6
	v_pk_add_f32 v[6:7], v[46:47], v[2:3]
	v_lshlrev_b32_e32 v11, 16, v10
	v_and_b32_e32 v10, 0xffff0000, v10
	v_add_f32_e32 v2, 0, v6
	v_add_f32_e32 v46, v7, v2
	v_mul_f32_e32 v2, 0xbfb8aa3b, v11
	v_mul_f32_e32 v3, 0xbfb8aa3b, v10
	v_exp_f32_e32 v2, v2
	v_exp_f32_e32 v3, v3
	s_nop 0
	v_pk_add_f32 v[2:3], v[2:3], 1.0 op_sel_hi:[1,0]
	s_nop 0
	v_div_scale_f32 v47, s[0:1], v3, v3, v10
	v_rcp_f32_e32 v62, v47
	s_nop 0
	v_fma_f32 v63, -v47, v62, 1.0
	v_fmac_f32_e32 v62, v63, v62
	v_div_scale_f32 v63, vcc, v10, v3, v10
	v_mul_f32_e32 v64, v63, v62
	v_fma_f32 v65, -v47, v64, v63
	v_fmac_f32_e32 v64, v65, v62
	v_fma_f32 v47, -v47, v64, v63
	v_div_fmas_f32 v47, v47, v62, v64
	v_div_fixup_f32 v3, v47, v3, v10
	v_div_scale_f32 v10, s[0:1], v2, v2, v11
	v_rcp_f32_e32 v47, v10
	s_mov_b32 s0, 0x3b000000
	v_fma_f32 v62, -v10, v47, 1.0
	v_fmac_f32_e32 v47, v62, v47
	v_div_scale_f32 v62, vcc, v11, v2, v11
	v_mul_f32_e32 v63, v62, v47
	v_fma_f32 v64, -v10, v63, v62
	v_fmac_f32_e32 v63, v64, v47
	v_fma_f32 v10, -v10, v63, v62
	v_div_fmas_f32 v10, v10, v47, v63
	v_div_fixup_f32 v2, v10, v2, v11
	v_add_f32_e32 v10, v44, v46
	v_add_f32_e32 v10, v45, v10
	v_add_f32_e32 v10, v12, v10
	v_add_f32_e32 v10, v13, v10
	v_add_f32_e32 v10, v36, v10
	v_add_f32_e32 v10, v37, v10
	v_mov_b32_e32 v11, v10
	s_nop 1
	v_permlane32_swap_b32_e32 v11, v10
	s_waitcnt lgkmcnt(0)
	v_add_f32_e32 v10, v10, v11
	v_mov_b32_e32 v11, v10
	s_nop 1
	v_permlane16_swap_b32_e32 v11, v10
	s_waitcnt lgkmcnt(0)
	v_add_f32_e32 v10, v10, v11
	s_waitcnt lgkmcnt(0)
	s_nop 1
	v_add_f32_dpp v10, v10, v10 row_ror:8 row_mask:0xf bank_mask:0xf
	s_waitcnt lgkmcnt(0)
	s_nop 1
	v_add_f32_dpp v10, v10, v10 row_ror:4 row_mask:0xf bank_mask:0xf
	s_waitcnt lgkmcnt(0)
	s_nop 1
	v_add_f32_dpp v10, v10, v10 quad_perm:[2,3,0,1] row_mask:0xf bank_mask:0xf
	s_waitcnt lgkmcnt(0)
	s_nop 1
	v_add_f32_dpp v10, v10, v10 quad_perm:[1,0,3,2] row_mask:0xf bank_mask:0xf
	v_mul_f32_e32 v10, 0x3b000000, v10
	v_pk_add_f32 v[46:47], v[6:7], v[10:11] op_sel_hi:[1,0] neg_lo:[0,1] neg_hi:[0,1]
	v_mov_b32_e32 v7, v34
	v_mov_b32_e32 v34, v47
	v_pk_add_f32 v[44:45], v[44:45], v[10:11] op_sel_hi:[1,0] neg_lo:[0,1] neg_hi:[0,1]
	v_mov_b32_e32 v6, v46
	v_pk_mul_f32 v[34:35], v[34:35], v[34:35]
	v_pk_add_f32 v[48:49], v[12:13], v[10:11] op_sel_hi:[1,0] neg_lo:[0,1] neg_hi:[0,1]
	v_pk_fma_f32 v[6:7], v[6:7], v[6:7], v[34:35]
	v_mov_b32_e32 v34, v44
	v_mov_b32_e32 v35, v32
	v_pk_mul_f32 v[12:13], v[48:49], v[48:49]
	v_pk_fma_f32 v[6:7], v[34:35], v[34:35], v[6:7]
	v_mov_b32_e32 v32, v45
	v_pk_fma_f32 v[6:7], v[32:33], v[32:33], v[6:7]
	v_mov_b32_e32 v32, v12
	v_mov_b32_e32 v33, v30
	v_pk_add_f32 v[32:33], v[32:33], v[6:7]
	v_pk_add_f32 v[6:7], v[36:37], v[10:11] op_sel_hi:[1,0] neg_lo:[0,1] neg_hi:[0,1]
	v_mov_b32_e32 v30, v13
	v_pk_mul_f32 v[10:11], v[6:7], v[6:7]
	v_pk_add_f32 v[12:13], v[30:31], v[32:33]
	v_mov_b32_e32 v30, v10
	v_mov_b32_e32 v31, v24
	v_pk_add_f32 v[12:13], v[30:31], v[12:13]
	v_mov_b32_e32 v24, v11
	v_pk_add_f32 v[10:11], v[24:25], v[12:13]
	v_mov_b32_e32 v13, v11
	v_mov_b32_e32 v12, v10
	s_nop 1
	v_permlane32_swap_b32_e32 v13, v11
	v_permlane32_swap_b32_e32 v12, v10
	v_pk_mul_f32 v[2:3], v[2:3], v[46:47]
	v_pk_mul_f32 v[8:9], v[8:9], v[44:45]
	v_pk_mul_f32 v[4:5], v[4:5], v[48:49]
	s_waitcnt lgkmcnt(0)
	v_pk_add_f32 v[10:11], v[10:11], v[12:13]
	v_mov_b32_e32 v13, v11
	v_mov_b32_e32 v12, v10
	s_nop 1
	v_permlane16_swap_b32_e32 v13, v11
	v_permlane16_swap_b32_e32 v12, v10
	s_waitcnt lgkmcnt(0)
	v_pk_add_f32 v[10:11], v[10:11], v[12:13]
	s_waitcnt lgkmcnt(0)
	s_nop 1
	v_add_f32_dpp v10, v10, v10 row_ror:8 row_mask:0xf bank_mask:0xf
	v_add_f32_dpp v11, v11, v11 row_ror:8 row_mask:0xf bank_mask:0xf
	s_waitcnt lgkmcnt(0)
	s_nop 1
	v_add_f32_dpp v10, v10, v10 row_ror:4 row_mask:0xf bank_mask:0xf
	v_add_f32_dpp v11, v11, v11 row_ror:4 row_mask:0xf bank_mask:0xf
	s_waitcnt lgkmcnt(0)
	s_nop 1
	v_add_f32_dpp v10, v10, v10 quad_perm:[2,3,0,1] row_mask:0xf bank_mask:0xf
	v_add_f32_dpp v11, v11, v11 quad_perm:[2,3,0,1] row_mask:0xf bank_mask:0xf
	s_waitcnt lgkmcnt(0)
	s_nop 1
	v_add_f32_dpp v10, v10, v10 quad_perm:[1,0,3,2] row_mask:0xf bank_mask:0xf
	v_add_f32_dpp v11, v11, v11 quad_perm:[1,0,3,2] row_mask:0xf bank_mask:0xf
	s_nop 0
	v_pk_fma_f32 v[24:25], v[10:11], s[0:1], v[194:195] op_sel_hi:[1,0,0]
	s_nop 0
	v_mul_f32_e32 v0, 0x4b800000, v25
	v_cmp_gt_f32_e64 s[6:7], s49, v25
	v_cmp_gt_f32_e32 vcc, s49, v24
	s_nop 0
	v_cndmask_b32_e64 v0, v25, v0, s[6:7]
	v_rsq_f32_e32 v0, v0
	s_nop 0
	v_mul_f32_e32 v10, 0x45800000, v0
	v_cndmask_b32_e64 v0, v0, v10, s[6:7]
	v_pk_mul_f32 v[10:11], v[14:15], v[0:1] op_sel_hi:[1,0]
	v_pk_mul_f32 v[12:13], v[16:17], v[0:1] op_sel_hi:[1,0]
	v_pk_mul_f32 v[14:15], v[18:19], v[0:1] op_sel_hi:[1,0]
	v_pk_mul_f32 v[16:17], v[22:23], v[0:1] op_sel_hi:[1,0]
	v_mul_f32_e32 v0, 0x4b800000, v24
	v_cndmask_b32_e32 v0, v24, v0, vcc
	v_rsq_f32_e32 v0, v0
	v_cvt_pk_bf16_f32 v10, v10, v11
	v_cvt_pk_bf16_f32 v11, v12, v13
	v_cvt_pk_bf16_f32 v12, v14, v15
	v_cvt_pk_bf16_f32 v13, v16, v17
	global_store_dwordx4 v[20:21], v[10:13], off
	s_nop 1
	v_mul_f32_e32 v10, 0x45800000, v0
	v_cndmask_b32_e32 v0, v0, v10, vcc
	v_mul_f32_e32 v10, 0xbfb8aa3b, v60
	v_mul_f32_e32 v11, 0xbfb8aa3b, v61
	v_exp_f32_e32 v10, v10
	v_exp_f32_e32 v11, v11
	v_pk_mul_f32 v[2:3], v[2:3], v[0:1] op_sel_hi:[1,0]
	v_pk_mul_f32 v[8:9], v[8:9], v[0:1] op_sel_hi:[1,0]
	v_pk_mul_f32 v[4:5], v[4:5], v[0:1] op_sel_hi:[1,0]
	v_pk_add_f32 v[10:11], v[10:11], 1.0 op_sel_hi:[1,0]
	v_cvt_pk_bf16_f32 v2, v2, v3
	v_div_scale_f32 v12, s[0:1], v11, v11, v61
	v_rcp_f32_e32 v13, v12
	v_cvt_pk_bf16_f32 v3, v8, v9
	v_cvt_pk_bf16_f32 v4, v4, v5
	v_fma_f32 v14, -v12, v13, 1.0
	v_fmac_f32_e32 v13, v14, v13
	v_div_scale_f32 v14, vcc, v61, v11, v61
	v_mul_f32_e32 v15, v14, v13
	v_fma_f32 v16, -v12, v15, v14
	v_fmac_f32_e32 v15, v16, v13
	v_fma_f32 v12, -v12, v15, v14
	v_div_fmas_f32 v12, v12, v13, v15
	v_div_fixup_f32 v11, v12, v11, v61
	v_div_scale_f32 v12, s[0:1], v10, v10, v60
	v_rcp_f32_e32 v13, v12
	s_nop 0
	v_fma_f32 v14, -v12, v13, 1.0
	v_fmac_f32_e32 v13, v14, v13
	v_div_scale_f32 v14, vcc, v60, v10, v60
	v_mul_f32_e32 v15, v14, v13
	v_fma_f32 v16, -v12, v15, v14
	v_fmac_f32_e32 v15, v16, v13
	v_fma_f32 v12, -v12, v15, v14
	v_div_fmas_f32 v12, v12, v13, v15
	v_div_fixup_f32 v10, v12, v10, v60
	v_pk_mul_f32 v[6:7], v[10:11], v[6:7]
	s_nop 0
	v_pk_mul_f32 v[6:7], v[6:7], v[0:1] op_sel_hi:[1,0]
	s_nop 0
	v_cvt_pk_bf16_f32 v5, v6, v7
	v_lshl_add_u64 v[6:7], s[14:15], 0, v[28:29]
	global_store_dwordx4 v[6:7], v[2:5], off
	s_nop 1
	v_add_u32_e32 v2, s20, v38
	v_cmp_le_i32_e32 vcc, s21, v2
	s_or_b64 s[18:19], vcc, s[18:19]
	s_andn2_b64 exec, exec, s[18:19]
	s_cbranch_execnz .LBB0_954
